# MLA loop: the tid<256 K-chunk predicate is wave-uniform, so the exec save/restore pairs became scalar branches
# baseline (speedup 1.0000x reference)
; template <int MODE>
; DI void attn_unit(LAS unsigned char* lds, const bf16_t* Qg, int ldq, const bf16_t* Kg, int ldk, const bf16_t* VTg, int ldvt, bf16_t* Og, int ldo,
;                   int q0, int NT, const float* gout, const float* relb, float lam, float osc, const float* qgain) {
;     ...
;         if (t + 1 < NT) AT_LSTORE(cur ^ 1, vnext);
;         __syncthreads();
;         vcur = vnext;
.LBB0_233:
	s_add_i32 s2, s11, 1
	s_cmp_lg_u32 s11, 2
	s_cselect_b32 s11, s2, 0
	s_mul_i32 s14, s11, 0x4400
	v_add_u32_e32 v0, s14, v162
	s_add_i32 s13, s13, 1
	s_mov_b64 s[2:3], 0xc000
	v_add_u32_e32 v0, 0x8800, v0
	v_lshl_add_u64 v[138:139], v[138:139], 0, s[2:3]
	v_lshl_add_u64 v[140:141], v[140:141], 0, s[2:3]
	s_cmp_eq_u32 s9, s13
	v_lshl_add_u64 v[142:143], v[142:143], 0, s[34:35]
	ds_write2_b64 v0, v[2:3], v[4:5] offset1:1
	s_waitcnt lgkmcnt(0)
	s_barrier
	s_cbranch_scc1 .LBB0_250

; #define LAS __attribute__((address_space(3)))
; #define MFMA32(a, b, c) __builtin_amdgcn_mfma_f32_32x32x16_bf16((a), (b), (c), 0, 0, 0)
; template <int MODE>
; DI void attn_unit(LAS unsigned char* lds, const bf16_t* Qg, int ldq, const bf16_t* Kg, int ldk, const bf16_t* VTg, int ldvt, bf16_t* Og, int ldo,
;                   int q0, int NT, const float* gout, const float* relb, float lam, float osc, const float* qgain) {
;     ...
;     auto pvdo = [&](const int vbi, const u32x4 (&pp)[4]) {
;         const LAS unsigned char* Vb = lds + VB0 + vbi * VBSZ + (r32 + (MODE == 2 ? mm * 64 : 0)) * VSTR + hi * 8;
; #pragma unroll
;         for (int d = 0; d < NDB; ++d)
; #pragma unroll
;             for (int ks = 0; ks < 4; ++ks) { const int kb = 32 * (ks >> 1) + 16 * (ks & 1);
;                 const s16x4 lo = *(const LAS s16x4*)(Vb + d * 32 * VSTR + kb * 2), hh = *(const LAS s16x4*)(Vb + d * 32 * VSTR + kb * 2 + 16);
;                 const bf16x8 vf = __builtin_shufflevector(lo, hh, 0, 1, 2, 3, 4, 5, 6, 7);
;                 o[d] = MFMA32(vf, __builtin_bit_cast(bf16x8, pp[ks]), o[d]); }
;     };
;     ...
;         if (t + 1 < NT) AT_GLOAD(AT_KEY0(t + 1));
;         const int key0 = AT_KEY0(t);
;         bool active;
;         if (MODE == 2) active = (NT - 1 - t) <= TD; else active = t < ntw;
;         bool alive = true;
;         if (MODE == 2) alive = !active || __any(R > -150.f);
;         if (skew && t >= 1 && (t - 1) < ntw) pvdo(vprev, pk);
.LBB0_236:
	s_cmp_eq_u64 s[40:41], 0
	s_cbranch_scc1 .LBB0_238
	global_load_dwordx4 v[100:103], v[140:141], off
.LBB0_238:
	global_load_dwordx4 v[2:5], v[142:143], off
	s_add_i32 s2, s13, 3
	s_cmp_le_i32 s2, s10
	s_cselect_b64 s[6:7], -1, 0
	s_and_b64 s[6:7], s[0:1], s[6:7]
	s_andn2_b64 vcc, exec, s[6:7]
	s_cbranch_vccnz .LBB0_240
	s_mul_i32 s3, s11, 0x4400
	s_addk_i32 s3, 0xbc00
	s_cmp_lg_u32 s11, 0
	s_cselect_b32 s3, s3, 0x8800
	v_add_u32_e32 v0, s3, v163
	v_add_u32_e32 v236, 0x8800, v0
	v_add_u32_e32 v237, 0x9800, v0
	ds_read2_b64 v[212:215], v236 offset1:2
	ds_read2_b64 v[216:219], v236 offset0:4 offset1:6
	ds_read2_b64 v[220:223], v236 offset0:8 offset1:10
	ds_read2_b64 v[224:227], v236 offset0:12 offset1:14
	s_waitcnt lgkmcnt(2)
	v_mfma_f32_32x32x16_bf16 v[32:47], v[212:215], v[68:71], v[32:47]
	v_mfma_f32_32x32x16_bf16 v[32:47], v[216:219], v[64:67], v[32:47]
	ds_read2_b64 v[212:215], v237 offset0:32 offset1:34
	ds_read2_b64 v[216:219], v237 offset0:36 offset1:38
	s_waitcnt lgkmcnt(2)
	v_mfma_f32_32x32x16_bf16 v[32:47], v[220:223], v[10:13], v[32:47]
	v_mfma_f32_32x32x16_bf16 v[32:47], v[224:227], v[6:9], v[32:47]
	ds_read2_b64 v[220:223], v237 offset0:40 offset1:42
	ds_read2_b64 v[224:227], v237 offset0:44 offset1:46
	s_waitcnt lgkmcnt(2)
	v_mfma_f32_32x32x16_bf16 v[16:31], v[212:215], v[68:71], v[16:31]
	v_mfma_f32_32x32x16_bf16 v[16:31], v[216:219], v[64:67], v[16:31]
	s_waitcnt lgkmcnt(0)
	v_mfma_f32_32x32x16_bf16 v[16:31], v[220:223], v[10:13], v[16:31]
	v_mfma_f32_32x32x16_bf16 v[16:31], v[224:227], v[6:9], v[16:31]

.LBB0_248:
	s_cmp_eq_u64 s[40:41], 0
	s_cbranch_scc1 .LBB0_233
	v_add3_u32 v0, s2, v165, v166
	ds_write_b128 v0, v[100:103]
	s_branch .LBB0_233
